# v10: k2=2 DMA rebalance + attention PV read batching + x-conversion unroll x4 + MoE gather loop unroll x4
# speedup vs baseline: 1.0037x; 1.0037x over previous
.LBB0_1199:
	s_or_b64 exec, exec, s[4:5]
	s_add_u32 s50, s84, 0x9c0000
	s_addc_u32 s51, s85, 0
	s_and_b64 vcc, exec, s[0:1]
	s_waitcnt lgkmcnt(0)
	s_barrier
	s_cbranch_vccnz .LBB0_1204
	v_readlane_b32 s0, v234, 0
	v_readlane_b32 s1, v234, 1
	s_mov_b32 s8, s0
	s_lshl_b32 s0, s0, 4
	s_lshl_b32 s1, s86, 1
	s_ashr_i32 s47, s46, 31
	s_add_i32 s0, s0, s1
	s_lshl_b32 s3, s82, 4
	s_lshl_b64 s[4:5], s[46:47], 10
	v_ashrrev_i32_e32 v1, 31, v0
	s_add_u32 s4, s84, s4
	v_lshlrev_b64 v[4:5], 4, v[0:1]
	s_addc_u32 s5, s85, s5
	v_cmp_eq_u32_e32 vcc, 0, v0
	v_lshl_add_u64 v[0:1], s[4:5], 0, v[4:5]
	s_mov_b64 s[4:5], 0xe400000
	s_ashr_i32 s81, s80, 31
	s_lshl_b32 s1, s8, 5
	s_lshl_b32 s8, s86, 2
	v_lshl_add_u64 v[2:3], s[68:69], 0, v[4:5]
	v_lshl_add_u64 v[0:1], v[0:1], 0, s[4:5]
	s_lshl_b64 s[4:5], s[80:81], 10
	s_add_i32 s8, s1, s8
	s_lshl_b32 s12, s82, 5
	v_mov_b32_e32 v8, 0
	s_mov_b32 s13, s46
	s_mul_i32 s16, s80, 3
	s_lshl_b32 s17, s12, 2
.Lgat4_top:
	s_add_i32 s18, s13, s16
	s_cmpk_lt_i32 s18, 0x4000
	s_cbranch_scc0 .Lgat4_done
	s_ashr_i32 s9, s8, 31
	s_lshl_b64 s[10:11], s[8:9], 2
	s_add_u32 s10, s6, s10
	s_addc_u32 s11, s7, s11
	s_add_u32 s20, s10, s17
	s_addc_u32 s21, s11, 0
	s_add_u32 s22, s20, s17
	s_addc_u32 s23, s21, 0
	s_add_u32 s24, s22, s17
	s_addc_u32 s25, s23, 0
	v_lshl_add_u64 v[42:43], v[0:1], 0, s[4:5]
	v_lshl_add_u64 v[44:45], v[42:43], 0, s[4:5]
	v_lshl_add_u64 v[46:47], v[44:45], 0, s[4:5]
	global_load_dwordx4 v[4:7], v8, s[10:11]
	global_load_dwordx4 v[18:21], v8, s[20:21]
	global_load_dwordx4 v[22:25], v8, s[22:23]
	global_load_dwordx4 v[26:29], v8, s[24:25]
	global_load_dwordx4 v[10:13], v[0:1], off
	global_load_dwordx4 v[30:33], v[42:43], off
	global_load_dwordx4 v[34:37], v[44:45], off
	global_load_dwordx4 v[38:41], v[46:47], off
	s_waitcnt vmcnt(4)
	v_lshlrev_b32_e32 v4, 2, v4
	v_lshlrev_b32_e32 v6, 2, v6
	ds_read_b32 v6, v6
	ds_read_b32 v4, v4
	v_lshlrev_b32_e32 v18, 2, v18
	v_lshlrev_b32_e32 v20, 2, v20
	ds_read_b32 v20, v20
	ds_read_b32 v18, v18
	v_lshlrev_b32_e32 v22, 2, v22
	v_lshlrev_b32_e32 v24, 2, v24
	ds_read_b32 v24, v24
	ds_read_b32 v22, v22
	v_lshlrev_b32_e32 v26, 2, v26
	v_lshlrev_b32_e32 v28, 2, v28
	ds_read_b32 v28, v28
	ds_read_b32 v26, v26
	s_waitcnt lgkmcnt(0)
	v_add_u32_e32 v6, v6, v7
	v_add_u32_e32 v4, v4, v5
	v_add_u32_e32 v20, v20, v21
	v_add_u32_e32 v18, v18, v19
	v_add_u32_e32 v24, v24, v25
	v_add_u32_e32 v22, v22, v23
	v_add_u32_e32 v28, v28, v29
	v_add_u32_e32 v26, v26, v27
	s_waitcnt vmcnt(0)
	v_ashrrev_i32_e32 v5, 31, v4
	v_ashrrev_i32_e32 v7, 31, v6
	v_lshlrev_b64 v[14:15], 10, v[4:5]
	v_lshlrev_b64 v[16:17], 10, v[6:7]
	v_lshl_add_u64 v[14:15], v[2:3], 0, v[14:15]
	v_lshl_add_u64 v[16:17], v[2:3], 0, v[16:17]
	global_store_dwordx4 v[14:15], v[10:13], off
	global_store_dwordx4 v[16:17], v[10:13], off
	s_ashr_i32 s1, s0, 31
	s_lshl_b64 s[14:15], s[0:1], 2
	s_add_u32 s14, s50, s14
	s_addc_u32 s15, s51, s15
	v_mov_b32_e32 v5, v6
	s_and_saveexec_b64 s[26:27], vcc
	global_store_dwordx2 v8, v[4:5], s[14:15]
	s_or_b64 exec, exec, s[26:27]
	s_add_i32 s0, s0, s3
	s_add_i32 s8, s8, s12
	s_add_i32 s13, s13, s80
	v_ashrrev_i32_e32 v19, 31, v18
	v_ashrrev_i32_e32 v21, 31, v20
	v_lshlrev_b64 v[14:15], 10, v[18:19]
	v_lshlrev_b64 v[16:17], 10, v[20:21]
	v_lshl_add_u64 v[14:15], v[2:3], 0, v[14:15]
	v_lshl_add_u64 v[16:17], v[2:3], 0, v[16:17]
	global_store_dwordx4 v[14:15], v[30:33], off
	global_store_dwordx4 v[16:17], v[30:33], off
	s_ashr_i32 s1, s0, 31
	s_lshl_b64 s[14:15], s[0:1], 2
	s_add_u32 s14, s50, s14
	s_addc_u32 s15, s51, s15
	v_mov_b32_e32 v19, v20
	s_and_saveexec_b64 s[26:27], vcc
	global_store_dwordx2 v8, v[18:19], s[14:15]
	s_or_b64 exec, exec, s[26:27]
	s_add_i32 s0, s0, s3
	s_add_i32 s8, s8, s12
	s_add_i32 s13, s13, s80
	v_ashrrev_i32_e32 v23, 31, v22
	v_ashrrev_i32_e32 v25, 31, v24
	v_lshlrev_b64 v[14:15], 10, v[22:23]
	v_lshlrev_b64 v[16:17], 10, v[24:25]
	v_lshl_add_u64 v[14:15], v[2:3], 0, v[14:15]
	v_lshl_add_u64 v[16:17], v[2:3], 0, v[16:17]
	global_store_dwordx4 v[14:15], v[34:37], off
	global_store_dwordx4 v[16:17], v[34:37], off
	s_ashr_i32 s1, s0, 31
	s_lshl_b64 s[14:15], s[0:1], 2
	s_add_u32 s14, s50, s14
	s_addc_u32 s15, s51, s15
	v_mov_b32_e32 v23, v24
	s_and_saveexec_b64 s[26:27], vcc
	global_store_dwordx2 v8, v[22:23], s[14:15]
	s_or_b64 exec, exec, s[26:27]
	s_add_i32 s0, s0, s3
	s_add_i32 s8, s8, s12
	s_add_i32 s13, s13, s80
	v_ashrrev_i32_e32 v27, 31, v26
	v_ashrrev_i32_e32 v29, 31, v28
	v_lshlrev_b64 v[14:15], 10, v[26:27]
	v_lshlrev_b64 v[16:17], 10, v[28:29]
	v_lshl_add_u64 v[14:15], v[2:3], 0, v[14:15]
	v_lshl_add_u64 v[16:17], v[2:3], 0, v[16:17]
	global_store_dwordx4 v[14:15], v[38:41], off
	global_store_dwordx4 v[16:17], v[38:41], off
	s_ashr_i32 s1, s0, 31
	s_lshl_b64 s[14:15], s[0:1], 2
	s_add_u32 s14, s50, s14
	s_addc_u32 s15, s51, s15
	v_mov_b32_e32 v27, v28
	s_and_saveexec_b64 s[26:27], vcc
	global_store_dwordx2 v8, v[26:27], s[14:15]
	s_or_b64 exec, exec, s[26:27]
	s_add_i32 s0, s0, s3
	s_add_i32 s8, s8, s12
	s_add_i32 s13, s13, s80
	v_lshl_add_u64 v[0:1], v[46:47], 0, s[4:5]
	s_branch .Lgat4_top
.Lgat4_done:
	s_cmpk_lt_i32 s13, 0x4000
	s_cbranch_scc1 .LBB0_1202
	s_branch .LBB0_1204
